# rowpass A: removed three vmcnt(0) waits that only waited on the row's own stores (loads were hoisted earlier)
# speedup vs baseline: 1.0079x; 1.0079x over previous
.LBB0_389:
	s_and_b32 s0, s14, 0x7ff
	s_cmpk_lt_i32 s14, 0x4000
	s_cselect_b32 s0, s0, s17
	v_lshl_or_b32 v152, s0, 9, v8
	v_lshl_add_u64 v[0:1], s[6:7], 0, v[152:153]
	v_mov_b32_e32 v2, v100
	v_mov_b32_e32 v3, v101
	v_lshl_add_u64 v[0:1], s[8:9], 0, v[16:17]
	v_add_co_u32_e32 v0, vcc, 0xc701000, v0
	s_mov_b32 s0, 0x3db504f3
	s_nop 0
	v_addc_co_u32_e32 v1, vcc, 0, v1, vcc
	v_mov_b32_e32 v4, v102
	v_mov_b32_e32 v5, v103
	s_add_i32 s14, s14, s80
	v_lshlrev_b32_e32 v4, 16, v4
	v_lshlrev_b32_e32 v6, 16, v5
	v_pk_mul_f32 v[6:7], v[2:3], v[6:7] op_sel:[1,0] op_sel_hi:[0,0]
	v_pk_fma_f32 v[18:19], v[2:3], v[4:5], v[6:7] neg_lo:[0,0,1] neg_hi:[0,0,1]
	v_pk_fma_f32 v[4:5], v[2:3], v[4:5], v[6:7] op_sel_hi:[1,0,1]
	s_nop 0
	v_cvt_pk_bf16_f32 v4, v18, v5
	flat_store_short v[0:1], v4
	flat_store_short_d16_hi v[0:1], v4 offset:128
	v_mov_b32_e32 v4, v104
	s_nop 0
	v_mov_b32_e32 v5, v105
	v_lshlrev_b32_e32 v4, 16, v4
	v_lshlrev_b32_e32 v6, 16, v5
	v_pk_mul_f32 v[6:7], v[2:3], v[6:7] op_sel:[1,0] op_sel_hi:[0,0]
	v_pk_fma_f32 v[18:19], v[2:3], v[4:5], v[6:7] neg_lo:[0,0,1] neg_hi:[0,0,1]
	v_pk_fma_f32 v[4:5], v[2:3], v[4:5], v[6:7] op_sel_hi:[1,0,1]
	s_nop 0
	v_cvt_pk_bf16_f32 v4, v18, v5
	flat_store_short v[0:1], v4 offset:256
	flat_store_short_d16_hi v[0:1], v4 offset:384
	v_mov_b32_e32 v4, v106
	s_nop 0
	v_mov_b32_e32 v5, v107
	v_lshlrev_b32_e32 v4, 16, v4
	v_lshlrev_b32_e32 v6, 16, v5
	v_pk_mul_f32 v[6:7], v[2:3], v[6:7] op_sel:[1,0] op_sel_hi:[0,0]
	v_pk_fma_f32 v[18:19], v[2:3], v[4:5], v[6:7] neg_lo:[0,0,1] neg_hi:[0,0,1]
	v_pk_fma_f32 v[4:5], v[2:3], v[4:5], v[6:7] op_sel_hi:[1,0,1]
	s_nop 0
	v_cvt_pk_bf16_f32 v4, v18, v5
	flat_store_short v[0:1], v4 offset:512
	flat_store_short_d16_hi v[0:1], v4 offset:640
	v_mov_b32_e32 v4, v108
	s_nop 0
	v_mov_b32_e32 v5, v109
	v_lshlrev_b32_e32 v4, 16, v4
	v_lshlrev_b32_e32 v6, 16, v5
	v_pk_mul_f32 v[6:7], v[2:3], v[6:7] op_sel:[1,0] op_sel_hi:[0,0]
	v_pk_fma_f32 v[18:19], v[2:3], v[4:5], v[6:7] neg_lo:[0,0,1] neg_hi:[0,0,1]
	v_pk_fma_f32 v[4:5], v[2:3], v[4:5], v[6:7] op_sel_hi:[1,0,1]
	s_nop 0
	v_cvt_pk_bf16_f32 v4, v18, v5
	flat_store_short v[0:1], v4 offset:768
	flat_store_short_d16_hi v[0:1], v4 offset:896
	v_mov_b32_e32 v4, v110
	s_nop 0
	v_mov_b32_e32 v5, v111
	v_lshlrev_b32_e32 v4, 16, v4
	v_lshlrev_b32_e32 v6, 16, v5
	v_pk_mul_f32 v[6:7], v[2:3], v[6:7] op_sel:[1,0] op_sel_hi:[0,0]
	v_pk_fma_f32 v[18:19], v[2:3], v[4:5], v[6:7] neg_lo:[0,0,1] neg_hi:[0,0,1]
	v_pk_fma_f32 v[4:5], v[2:3], v[4:5], v[6:7] op_sel_hi:[1,0,1]
	s_nop 0
	v_mov_b32_e32 v19, v5
	v_pk_mul_f32 v[4:5], v[18:19], s[0:1] op_sel_hi:[1,0]
	s_nop 0
	v_cvt_pk_bf16_f32 v4, v4, v5
	flat_store_short v[0:1], v4 offset:1024
	flat_store_short_d16_hi v[0:1], v4 offset:1152
	v_mov_b32_e32 v4, v112
	s_nop 0
	v_mov_b32_e32 v5, v113
	v_lshlrev_b32_e32 v4, 16, v4
	v_lshlrev_b32_e32 v6, 16, v5
	v_pk_mul_f32 v[6:7], v[2:3], v[6:7] op_sel:[1,0] op_sel_hi:[0,0]
	v_pk_fma_f32 v[18:19], v[2:3], v[4:5], v[6:7] neg_lo:[0,0,1] neg_hi:[0,0,1]
	v_pk_fma_f32 v[4:5], v[2:3], v[4:5], v[6:7] op_sel_hi:[1,0,1]
	s_nop 0
	v_mov_b32_e32 v19, v5
	v_pk_mul_f32 v[4:5], v[18:19], s[0:1] op_sel_hi:[1,0]
	s_nop 0
	v_cvt_pk_bf16_f32 v4, v4, v5
	flat_store_short v[0:1], v4 offset:1280
	flat_store_short_d16_hi v[0:1], v4 offset:1408
	v_mov_b32_e32 v4, v114
	s_nop 0
	v_mov_b32_e32 v5, v115
	v_lshlrev_b32_e32 v4, 16, v4
	v_lshlrev_b32_e32 v6, 16, v5
	v_pk_mul_f32 v[6:7], v[2:3], v[6:7] op_sel:[1,0] op_sel_hi:[0,0]
	v_pk_fma_f32 v[18:19], v[2:3], v[4:5], v[6:7] neg_lo:[0,0,1] neg_hi:[0,0,1]
	v_pk_fma_f32 v[4:5], v[2:3], v[4:5], v[6:7] op_sel_hi:[1,0,1]
	s_nop 0
	v_mov_b32_e32 v19, v5
	v_pk_mul_f32 v[4:5], v[18:19], s[0:1] op_sel_hi:[1,0]
	s_nop 0
	v_cvt_pk_bf16_f32 v4, v4, v5
	flat_store_short v[0:1], v4 offset:1536
	flat_store_short_d16_hi v[0:1], v4 offset:1664
	v_mov_b32_e32 v4, v116
	s_nop 0
	v_mov_b32_e32 v5, v117
	v_lshlrev_b32_e32 v4, 16, v4
	v_lshlrev_b32_e32 v6, 16, v5
	v_pk_mul_f32 v[6:7], v[2:3], v[6:7] op_sel:[1,0] op_sel_hi:[0,0]
	v_pk_fma_f32 v[18:19], v[2:3], v[4:5], v[6:7] neg_lo:[0,0,1] neg_hi:[0,0,1]
	v_pk_fma_f32 v[2:3], v[2:3], v[4:5], v[6:7] op_sel_hi:[1,0,1]
	s_nop 0
	v_mov_b32_e32 v19, v3
	v_pk_mul_f32 v[2:3], v[18:19], s[0:1] op_sel_hi:[1,0]
	s_mul_i32 s0, s3, 0x14000
	s_add_u32 s8, s8, s0
	s_mul_hi_i32 s0, s80, 0x2800
	s_addc_u32 s9, s9, s0
	v_cvt_pk_bf16_f32 v2, v2, v3
	s_cmpk_gt_i32 s14, 0x43ff
	flat_store_short v[0:1], v2 offset:1792
	flat_store_short_d16_hi v[0:1], v2 offset:1920
	s_cbranch_scc1 .LBB0_394
.LBB0_390:
	s_and_b32 s0, s14, 0x7ff
	s_cmpk_lt_i32 s14, 0x4000
	s_cselect_b32 s0, s0, s17
	v_lshl_or_b32 v152, s0, 9, v8
	v_lshl_add_u64 v[120:121], s[6:7], 0, v[152:153]
	global_load_dwordx2 v[100:101], v[120:121], off
	v_lshl_add_u64 v[118:119], s[8:9], 0, v[16:17]
	v_add_co_u32_e32 v118, vcc, 0xc701000, v118
	s_nop 1
	v_addc_co_u32_e32 v119, vcc, 0, v119, vcc
	global_load_ushort v102, v[118:119], off
	global_load_ushort v103, v[118:119], off offset:128
	global_load_ushort v104, v[118:119], off offset:256
	global_load_ushort v105, v[118:119], off offset:384
	global_load_ushort v106, v[118:119], off offset:512
	global_load_ushort v107, v[118:119], off offset:640
	global_load_ushort v108, v[118:119], off offset:768
	global_load_ushort v109, v[118:119], off offset:896
	global_load_ushort v110, v[118:119], off offset:1024
	global_load_ushort v111, v[118:119], off offset:1152
	global_load_ushort v112, v[118:119], off offset:1280
	global_load_ushort v113, v[118:119], off offset:1408
	global_load_ushort v114, v[118:119], off offset:1536
	global_load_ushort v115, v[118:119], off offset:1664
	global_load_ushort v116, v[118:119], off offset:1792
	global_load_ushort v117, v[118:119], off offset:1920
	v_lshl_add_u64 v[18:19], s[8:9], 0, v[14:15]
	v_add_co_u32_e32 v44, vcc, 0xc700000, v18
	s_cmpk_gt_i32 s14, 0x3fff
	s_nop 0
	v_addc_co_u32_e32 v45, vcc, 0, v19, vcc
	flat_load_dwordx4 v[0:3], v[44:45] offset:3072
	flat_load_dwordx4 v[4:7], v[44:45] offset:2048
	s_cselect_b64 s[10:11], -1, 0
	s_add_i32 s0, s14, 0xffffc000
	s_lshl_b64 s[4:5], s[0:1], 12
	s_add_u32 s12, s15, s4
	s_addc_u32 s13, s16, s5
	s_cmpk_lt_i32 s14, 0x4000
	v_lshlrev_b32_e32 v152, 2, v8
	s_waitcnt vmcnt(0) lgkmcnt(0)
	v_lshlrev_b32_e32 v20, 16, v0
	v_lshlrev_b32_e32 v50, 16, v4
	v_and_b32_e32 v21, 0xffff0000, v0
	v_and_b32_e32 v51, 0xffff0000, v4
	v_add_f32_e32 v0, 0, v50
	v_lshlrev_b32_e32 v46, 16, v5
	v_add_f32_e32 v0, v0, v51
	v_and_b32_e32 v47, 0xffff0000, v5
	v_add_f32_e32 v0, v0, v46
	v_lshlrev_b32_e32 v48, 16, v6
	v_add_f32_e32 v0, v0, v47
	v_and_b32_e32 v49, 0xffff0000, v6
	v_add_f32_e32 v0, v0, v48
	v_lshlrev_b32_e32 v28, 16, v7
	v_add_f32_e32 v0, v0, v49
	v_and_b32_e32 v29, 0xffff0000, v7
	v_add_f32_e32 v0, v0, v28
	v_add_f32_e32 v0, v0, v29
	v_add_f32_e32 v0, v0, v20
	v_lshlrev_b32_e32 v22, 16, v1
	v_add_f32_e32 v0, v0, v21
	v_and_b32_e32 v23, 0xffff0000, v1
	v_add_f32_e32 v0, v0, v22
	v_lshlrev_b32_e32 v24, 16, v2
	v_add_f32_e32 v0, v0, v23
	v_and_b32_e32 v25, 0xffff0000, v2
	v_add_f32_e32 v0, v0, v24
	v_lshlrev_b32_e32 v26, 16, v3
	v_add_f32_e32 v0, v0, v25
	v_and_b32_e32 v27, 0xffff0000, v3
	v_add_f32_e32 v0, v0, v26
	v_add_f32_e32 v0, v0, v27
	ds_bpermute_b32 v1, v9, v0
	s_waitcnt lgkmcnt(0)
	v_add_f32_e32 v0, v0, v1
	ds_bpermute_b32 v1, v30, v0
	s_waitcnt lgkmcnt(0)
	v_add_f32_e32 v0, v0, v1
	ds_bpermute_b32 v1, v31, v0
	s_waitcnt lgkmcnt(0)
	v_add_f32_e32 v0, v0, v1
	ds_bpermute_b32 v1, v32, v0
	s_waitcnt lgkmcnt(0)
	v_add_f32_e32 v0, v0, v1
	ds_bpermute_b32 v1, v33, v0
	s_waitcnt lgkmcnt(0)
	v_add_f32_e32 v35, v0, v1
	ds_bpermute_b32 v52, v34, v35
	v_mov_b32_e32 v0, v68
	v_mov_b32_e32 v1, v69
	v_mov_b32_e32 v2, v70
	v_mov_b32_e32 v3, v71
	v_mov_b32_e32 v36, v72
	v_mov_b32_e32 v37, v73
	v_mov_b32_e32 v38, v74
	v_mov_b32_e32 v39, v75
	v_mov_b32_e32 v4, v76
	v_mov_b32_e32 v5, v77
	v_mov_b32_e32 v6, v78
	v_mov_b32_e32 v7, v79
	v_mov_b32_e32 v40, v80
	v_mov_b32_e32 v41, v81
	v_mov_b32_e32 v42, v82
	v_mov_b32_e32 v43, v83
	s_waitcnt lgkmcnt(0)
	v_add_f32_e32 v35, v35, v52
	v_mul_f32_e32 v52, 0x3a800000, v35
	v_pk_add_f32 v[50:51], v[50:51], v[52:53] op_sel_hi:[1,0] neg_lo:[0,1] neg_hi:[0,1]
	v_pk_add_f32 v[46:47], v[46:47], v[52:53] op_sel_hi:[1,0] neg_lo:[0,1] neg_hi:[0,1]
	v_pk_add_f32 v[54:55], v[28:29], v[52:53] op_sel_hi:[1,0] neg_lo:[0,1] neg_hi:[0,1]
	v_pk_mul_f32 v[28:29], v[50:51], v[50:51]
	v_pk_add_f32 v[48:49], v[48:49], v[52:53] op_sel_hi:[1,0] neg_lo:[0,1] neg_hi:[0,1]
	v_pk_add_f32 v[20:21], v[20:21], v[52:53] op_sel_hi:[1,0] neg_lo:[0,1] neg_hi:[0,1]
	v_pk_add_f32 v[22:23], v[22:23], v[52:53] op_sel_hi:[1,0] neg_lo:[0,1] neg_hi:[0,1]
	v_pk_add_f32 v[24:25], v[24:25], v[52:53] op_sel_hi:[1,0] neg_lo:[0,1] neg_hi:[0,1]
	v_pk_add_f32 v[26:27], v[26:27], v[52:53] op_sel_hi:[1,0] neg_lo:[0,1] neg_hi:[0,1]
	v_pk_mul_f32 v[52:53], v[46:47], v[46:47]
	v_add_f32_e32 v28, v28, v29
	v_add_f32_e32 v28, v52, v28
	v_pk_mul_f32 v[56:57], v[48:49], v[48:49]
	v_add_f32_e32 v28, v53, v28
	v_add_f32_e32 v28, v56, v28
	v_pk_mul_f32 v[58:59], v[54:55], v[54:55]
	v_add_f32_e32 v28, v57, v28
	v_add_f32_e32 v28, v58, v28
	v_pk_mul_f32 v[60:61], v[20:21], v[20:21]
	v_add_f32_e32 v28, v59, v28
	v_add_f32_e32 v28, v60, v28
	v_pk_mul_f32 v[62:63], v[22:23], v[22:23]
	v_add_f32_e32 v28, v61, v28
	v_add_f32_e32 v28, v62, v28
	v_pk_mul_f32 v[64:65], v[24:25], v[24:25]
	v_add_f32_e32 v28, v63, v28
	v_add_f32_e32 v28, v64, v28
	v_pk_mul_f32 v[66:67], v[26:27], v[26:27]
	v_add_f32_e32 v28, v65, v28
	v_add_f32_e32 v28, v66, v28
	v_add_f32_e32 v28, v67, v28
	ds_bpermute_b32 v29, v9, v28
	s_waitcnt lgkmcnt(0)
	v_add_f32_e32 v28, v28, v29
	ds_bpermute_b32 v29, v30, v28
	s_waitcnt lgkmcnt(0)
	v_add_f32_e32 v28, v28, v29
	ds_bpermute_b32 v29, v31, v28
	s_waitcnt lgkmcnt(0)
	v_add_f32_e32 v28, v28, v29
	ds_bpermute_b32 v29, v32, v28
	s_waitcnt lgkmcnt(0)
	v_add_f32_e32 v28, v28, v29
	ds_bpermute_b32 v29, v33, v28
	s_waitcnt lgkmcnt(0)
	v_add_f32_e32 v28, v28, v29
	ds_bpermute_b32 v29, v34, v28
	s_waitcnt lgkmcnt(0)
	v_add_f32_e32 v28, v28, v29
	v_fmamk_f32 v28, v28, 0x3a800000, v183
	v_mul_f32_e32 v29, 0x4f800000, v28
	v_cmp_gt_f32_e32 vcc, s87, v28
	s_nop 1
	v_cndmask_b32_e32 v28, v28, v29, vcc
	v_sqrt_f32_e32 v29, v28
	s_nop 0
	v_add_u32_e32 v35, -1, v29
	v_add_u32_e32 v52, 1, v29
	v_fma_f32 v53, -v35, v29, v28
	v_fma_f32 v56, -v52, v29, v28
	v_cmp_ge_f32_e64 s[4:5], 0, v53
	s_nop 1
	v_cndmask_b32_e64 v29, v29, v35, s[4:5]
	v_cmp_lt_f32_e64 s[4:5], 0, v56
	s_nop 1
	v_cndmask_b32_e64 v29, v29, v52, s[4:5]
	v_mul_f32_e32 v35, 0x37800000, v29
	v_cndmask_b32_e32 v29, v29, v35, vcc
	v_cmp_class_f32_e32 vcc, v28, v189
	s_nop 1
	v_cndmask_b32_e32 v28, v29, v28, vcc
	v_div_scale_f32 v29, s[4:5], v28, v28, 1.0
	v_rcp_f32_e32 v35, v29
	v_div_scale_f32 v52, vcc, 1.0, v28, 1.0
	v_fma_f32 v53, -v29, v35, 1.0
	v_fmac_f32_e32 v35, v53, v35
	v_mul_f32_e32 v53, v52, v35
	v_fma_f32 v56, -v29, v53, v52
	v_fmac_f32_e32 v53, v56, v35
	v_fma_f32 v29, -v29, v53, v52
	v_div_fmas_f32 v29, v29, v35, v53
	v_div_fixup_f32 v28, v29, v28, 1.0
	v_pk_mul_f32 v[50:51], v[50:51], v[28:29] op_sel_hi:[1,0]
	v_pk_mul_f32 v[48:49], v[48:49], v[28:29] op_sel_hi:[1,0]
	v_pk_mul_f32 v[46:47], v[46:47], v[28:29] op_sel_hi:[1,0]
	v_pk_mul_f32 v[52:53], v[54:55], v[28:29] op_sel_hi:[1,0]
	v_pk_fma_f32 v[4:5], v[0:1], v[50:51], v[4:5]
	v_pk_fma_f32 v[0:1], v[36:37], v[48:49], v[40:41]
	v_pk_fma_f32 v[6:7], v[2:3], v[46:47], v[6:7]
	v_pk_fma_f32 v[2:3], v[38:39], v[52:53], v[42:43]
	v_cvt_pk_bf16_f32 v36, v4, v5
	v_cvt_pk_bf16_f32 v37, v6, v7
	v_cvt_pk_bf16_f32 v38, v0, v1
	v_cvt_pk_bf16_f32 v39, v2, v3
	flat_store_dwordx4 v[44:45], v[36:39] offset:2048
	s_cbranch_scc1 .LBB0_392
	s_nop 0
	v_lshl_add_u64 v[36:37], s[12:13], 0, v[152:153]
	flat_store_dwordx4 v[36:37], v[4:7] nt
	flat_store_dwordx4 v[36:37], v[0:3] offset:16 nt
.LBB0_392:
	s_nop 1
	v_mov_b32_e32 v0, v84
	v_mov_b32_e32 v1, v85
	v_mov_b32_e32 v2, v86
	v_mov_b32_e32 v3, v87
	s_nop 0
	v_mov_b32_e32 v4, v88
	v_mov_b32_e32 v5, v89
	v_mov_b32_e32 v6, v90
	v_mov_b32_e32 v7, v91
	v_mov_b32_e32 v36, v92
	v_mov_b32_e32 v37, v93
	v_mov_b32_e32 v38, v94
	v_mov_b32_e32 v39, v95
	v_mov_b32_e32 v40, v96
	v_mov_b32_e32 v41, v97
	v_mov_b32_e32 v42, v98
	v_mov_b32_e32 v43, v99
	s_mov_b64 s[4:5], 0xc700c00
	v_mov_b32_e32 v29, v28
	v_lshl_add_u64 v[44:45], v[18:19], 0, s[4:5]
	v_pk_mul_f32 v[18:19], v[20:21], v[28:29]
	v_pk_mul_f32 v[20:21], v[24:25], v[28:29]
	v_pk_mul_f32 v[22:23], v[22:23], v[28:29]
	v_pk_mul_f32 v[24:25], v[26:27], v[28:29]
	s_andn2_b64 vcc, exec, s[10:11]
	v_pk_fma_f32 v[4:5], v[18:19], v[4:5], v[36:37]
	v_pk_fma_f32 v[0:1], v[20:21], v[0:1], v[40:41]
	v_pk_fma_f32 v[6:7], v[22:23], v[6:7], v[38:39]
	v_pk_fma_f32 v[2:3], v[24:25], v[2:3], v[42:43]
	v_cvt_pk_bf16_f32 v18, v4, v5
	v_cvt_pk_bf16_f32 v19, v6, v7
	v_cvt_pk_bf16_f32 v20, v0, v1
	v_cvt_pk_bf16_f32 v21, v2, v3
	flat_store_dwordx4 v[44:45], v[18:21]
	s_cbranch_vccnz .LBB0_389
	s_nop 0
	v_lshl_add_u64 v[18:19], s[12:13], 0, v[152:153]
	flat_store_dwordx4 v[18:19], v[4:7] offset:2048 nt
	flat_store_dwordx4 v[18:19], v[0:3] offset:2064 nt
	s_branch .LBB0_389
